# ResLN epilogue of the mixer/cross-attention output projections: residual loads prefetched four rows ahead instead of three
# baseline (speedup 1.0000x reference)
; __device__ __forceinline__ unsigned cvt_pk_bf16(float lo, float hi) { unsigned r; asm volatile("v_cvt_pk_bf16_f32 %0, %1, %2" : "=v"(r) : "v"(lo), "v"(hi)); return r; }
;     __device__ __forceinline__ void operator()(f32x4 (&acc)[2][2][4][2], const Unit& u, int wr, int wc, int fr, int fq) const {
;     ...
;                 for (int n = 0; n < 2; ++n) { const f32x4 g4 = *(const f32x4*)(gp + col0 + bj * HALF + n * 16), b4 = *(const f32x4*)(bp + col0 + bj * HALF + n * 16);
;                     u32x2 told[4];
;                     if (!Xin) {
; #pragma unroll
;                         for (int m = 0; m < 4; ++m) told[m] = *(const u32x2*)(YB + (size_t)(row0 + ai * HALF + m * 16) * 1024 + col0 + bj * HALF + n * 16);
;                     }
; #pragma unroll
;                     for (int m = 0; m < 4; ++m) { const size_t off = (size_t)(row0 + ai * HALF + m * 16) * 1024 + col0 + bj * HALF + n * 16;
;                         f32x4 yo;
;                         if (Xin) yo = *(const f32x4*)(Xin + off);
;                         else { const u32x2 t = told[m]; yo = (f32x4){__uint_as_float(t.x << 16), __uint_as_float(t.x & 0xffff0000u), __uint_as_float(t.y << 16), __uint_as_float(t.y & 0xffff0000u)}; }
;                         const f32x4 yn = ((yo - mu[m]) * rs[m] * g4 + b4) * alpha + acc[ai][bj][m][n];
;                         acc[ai][bj][m][n] = yn;
;                         if (Yout) *(f32x4*)(Yout + off) = yn;
;                         else { u32x2 w; w.x = cvt_pk_bf16(yn[0], yn[1]); w.y = cvt_pk_bf16(yn[2], yn[3]); *(u32x2*)(YB + off) = w; } } } }
.Lres_fast_a:
	s_lshl_b32 s39, s46, 8
	s_mov_b64 s[4:5], s[68:69]
	s_mov_b64 s[16:17], s[68:69]
	v_add_u32_e32 v223, s39, v171
	v_lshl_or_b32 v222, s48, 8, v248
	v_lshlrev_b32_e32 v221, 3, v223
	v_lshlrev_b32_e32 v216, 1, v222
	v_lshl_add_u32 v223, v223, 11, v216
	v_lshlrev_b32_e32 v222, 2, v222
	global_load_dwordx4 v[128:131], v222, s[22:23] offset:0
	global_load_dwordx4 v[150:153], v222, s[24:25] offset:0
	global_load_dwordx4 v[132:135], v222, s[22:23] offset:64
	global_load_dwordx4 v[154:157], v222, s[24:25] offset:64
	global_load_dwordx4 v[136:139], v222, s[22:23] offset:512
	global_load_dwordx4 v[158:161], v222, s[24:25] offset:512
	global_load_dwordx4 v[146:149], v222, s[22:23] offset:576
	global_load_dwordx4 v[174:177], v222, s[24:25] offset:576
	global_load_dwordx2 v[162:163], v221, s[88:89] offset:0
	global_load_dwordx2 v[184:185], v223, s[4:5] offset:0
	global_load_dwordx2 v[186:187], v223, s[4:5] offset:32
	global_load_dwordx2 v[188:189], v223, s[4:5] offset:256
	global_load_dwordx2 v[190:191], v223, s[4:5] offset:288
	s_add_u32 s4, s4, 0x8000
	s_addc_u32 s5, s5, 0
	global_load_dwordx2 v[178:179], v221, s[88:89] offset:128
	global_load_dwordx2 v[192:193], v223, s[4:5] offset:0
	global_load_dwordx2 v[194:195], v223, s[4:5] offset:32
	global_load_dwordx2 v[196:197], v223, s[4:5] offset:256
	global_load_dwordx2 v[198:199], v223, s[4:5] offset:288
	s_add_u32 s4, s4, 0x8000
	s_addc_u32 s5, s5, 0
	global_load_dwordx2 v[180:181], v221, s[88:89] offset:256
	global_load_dwordx2 v[200:201], v223, s[4:5] offset:0
	global_load_dwordx2 v[202:203], v223, s[4:5] offset:32
	global_load_dwordx2 v[204:205], v223, s[4:5] offset:256
	global_load_dwordx2 v[206:207], v223, s[4:5] offset:288
	s_add_u32 s4, s4, 0x8000
	s_addc_u32 s5, s5, 0
	global_load_dwordx2 v[182:183], v221, s[88:89] offset:384
	global_load_dwordx2 v[208:209], v223, s[4:5] offset:0
	global_load_dwordx2 v[210:211], v223, s[4:5] offset:32
	global_load_dwordx2 v[212:213], v223, s[4:5] offset:256
	global_load_dwordx2 v[214:215], v223, s[4:5] offset:288
	s_add_u32 s4, s4, 0x28000
	s_addc_u32 s5, s5, 0
	s_waitcnt vmcnt(15)
	v_lshlrev_b32_e32 v216, 16, v184
	v_and_b32_e32 v217, 0xffff0000, v184
	v_lshlrev_b32_e32 v184, 16, v185
	v_and_b32_e32 v185, 0xffff0000, v185
	v_sub_f32_e32 v216, v216, v162
	v_sub_f32_e32 v217, v217, v162
	v_sub_f32_e32 v184, v184, v162
	v_sub_f32_e32 v185, v185, v162
	v_pk_mul_f32 v[216:217], v[162:163], v[216:217] op_sel:[1,0]
	v_pk_mul_f32 v[184:185], v[162:163], v[184:185] op_sel:[1,0]
	v_pk_fma_f32 v[216:217], v[128:129], v[216:217], v[150:151]
	v_pk_fma_f32 v[184:185], v[130:131], v[184:185], v[152:153]
	v_pk_fma_f32 v[124:125], v[216:217], s[90:91], v[124:125] op_sel_hi:[1,0,1]
	v_pk_fma_f32 v[126:127], v[184:185], s[90:91], v[126:127] op_sel_hi:[1,0,1]
	v_cvt_pk_bf16_f32 v216, v124, v125
	v_cvt_pk_bf16_f32 v217, v126, v127
	global_store_dwordx2 v223, v[216:217], s[16:17] offset:0
	v_lshlrev_b32_e32 v218, 16, v186
	v_and_b32_e32 v219, 0xffff0000, v186
	v_lshlrev_b32_e32 v186, 16, v187
	v_and_b32_e32 v187, 0xffff0000, v187
	v_sub_f32_e32 v218, v218, v162
	v_sub_f32_e32 v219, v219, v162
	v_sub_f32_e32 v186, v186, v162
	v_sub_f32_e32 v187, v187, v162
	v_pk_mul_f32 v[218:219], v[162:163], v[218:219] op_sel:[1,0]
	v_pk_mul_f32 v[186:187], v[162:163], v[186:187] op_sel:[1,0]
	v_pk_fma_f32 v[218:219], v[132:133], v[218:219], v[154:155]
	v_pk_fma_f32 v[186:187], v[134:135], v[186:187], v[156:157]
	v_pk_fma_f32 v[108:109], v[218:219], s[90:91], v[108:109] op_sel_hi:[1,0,1]
	v_pk_fma_f32 v[110:111], v[186:187], s[90:91], v[110:111] op_sel_hi:[1,0,1]
	v_cvt_pk_bf16_f32 v218, v108, v109
	v_cvt_pk_bf16_f32 v219, v110, v111
	global_store_dwordx2 v223, v[218:219], s[16:17] offset:32
	v_lshlrev_b32_e32 v216, 16, v188
	v_and_b32_e32 v217, 0xffff0000, v188
	v_lshlrev_b32_e32 v188, 16, v189
	v_and_b32_e32 v189, 0xffff0000, v189
	v_sub_f32_e32 v216, v216, v162
	v_sub_f32_e32 v217, v217, v162
	v_sub_f32_e32 v188, v188, v162
	v_sub_f32_e32 v189, v189, v162
	v_pk_mul_f32 v[216:217], v[162:163], v[216:217] op_sel:[1,0]
	v_pk_mul_f32 v[188:189], v[162:163], v[188:189] op_sel:[1,0]
	v_pk_fma_f32 v[216:217], v[136:137], v[216:217], v[158:159]
	v_pk_fma_f32 v[188:189], v[138:139], v[188:189], v[160:161]
	v_pk_fma_f32 v[92:93], v[216:217], s[90:91], v[92:93] op_sel_hi:[1,0,1]
	v_pk_fma_f32 v[94:95], v[188:189], s[90:91], v[94:95] op_sel_hi:[1,0,1]
	v_cvt_pk_bf16_f32 v216, v92, v93
	v_cvt_pk_bf16_f32 v217, v94, v95
	global_store_dwordx2 v223, v[216:217], s[16:17] offset:256
	v_lshlrev_b32_e32 v218, 16, v190
	v_and_b32_e32 v219, 0xffff0000, v190
	v_lshlrev_b32_e32 v190, 16, v191
	v_and_b32_e32 v191, 0xffff0000, v191
	v_sub_f32_e32 v218, v218, v162
	v_sub_f32_e32 v219, v219, v162
	v_sub_f32_e32 v190, v190, v162
	v_sub_f32_e32 v191, v191, v162
	v_pk_mul_f32 v[218:219], v[162:163], v[218:219] op_sel:[1,0]
	v_pk_mul_f32 v[190:191], v[162:163], v[190:191] op_sel:[1,0]
	v_pk_fma_f32 v[218:219], v[146:147], v[218:219], v[174:175]
	v_pk_fma_f32 v[190:191], v[148:149], v[190:191], v[176:177]
	v_pk_fma_f32 v[76:77], v[218:219], s[90:91], v[76:77] op_sel_hi:[1,0,1]
	v_pk_fma_f32 v[78:79], v[190:191], s[90:91], v[78:79] op_sel_hi:[1,0,1]
	v_cvt_pk_bf16_f32 v218, v76, v77
	v_cvt_pk_bf16_f32 v219, v78, v79
	global_store_dwordx2 v223, v[218:219], s[16:17] offset:288
	s_add_u32 s16, s16, 0x8000
	s_addc_u32 s17, s17, 0
	global_load_dwordx2 v[162:163], v221, s[88:89] offset:1024
	global_load_dwordx2 v[184:185], v223, s[4:5] offset:0
	global_load_dwordx2 v[186:187], v223, s[4:5] offset:32
	global_load_dwordx2 v[188:189], v223, s[4:5] offset:256
	global_load_dwordx2 v[190:191], v223, s[4:5] offset:288
	s_add_u32 s4, s4, 0x8000
	s_addc_u32 s5, s5, 0
	s_waitcnt vmcnt(19)
; __device__ __forceinline__ unsigned cvt_pk_bf16(float lo, float hi) { unsigned r; asm volatile("v_cvt_pk_bf16_f32 %0, %1, %2" : "=v"(r) : "v"(lo), "v"(hi)); return r; }
;     __device__ __forceinline__ void operator()(f32x4 (&acc)[2][2][4][2], const Unit& u, int wr, int wc, int fr, int fq) const {
;     ...
;                 for (int n = 0; n < 2; ++n) { const f32x4 g4 = *(const f32x4*)(gp + col0 + bj * HALF + n * 16), b4 = *(const f32x4*)(bp + col0 + bj * HALF + n * 16);
;                     u32x2 told[4];
;                     if (!Xin) {
; #pragma unroll
;                         for (int m = 0; m < 4; ++m) told[m] = *(const u32x2*)(YB + (size_t)(row0 + ai * HALF + m * 16) * 1024 + col0 + bj * HALF + n * 16);
;                     }
; #pragma unroll
;                     for (int m = 0; m < 4; ++m) { const size_t off = (size_t)(row0 + ai * HALF + m * 16) * 1024 + col0 + bj * HALF + n * 16;
;                         f32x4 yo;
;                         if (Xin) yo = *(const f32x4*)(Xin + off);
;                         else { const u32x2 t = told[m]; yo = (f32x4){__uint_as_float(t.x << 16), __uint_as_float(t.x & 0xffff0000u), __uint_as_float(t.y << 16), __uint_as_float(t.y & 0xffff0000u)}; }
;                         const f32x4 yn = ((yo - mu[m]) * rs[m] * g4 + b4) * alpha + acc[ai][bj][m][n];
;                         acc[ai][bj][m][n] = yn;
;                         if (Yout) *(f32x4*)(Yout + off) = yn;
;                         else { u32x2 w; w.x = cvt_pk_bf16(yn[0], yn[1]); w.y = cvt_pk_bf16(yn[2], yn[3]); *(u32x2*)(YB + off) = w; } } } }
	v_lshlrev_b32_e32 v216, 16, v192
	v_and_b32_e32 v217, 0xffff0000, v192
	v_lshlrev_b32_e32 v192, 16, v193
	v_and_b32_e32 v193, 0xffff0000, v193
	v_sub_f32_e32 v216, v216, v178
	v_sub_f32_e32 v217, v217, v178
	v_sub_f32_e32 v192, v192, v178
	v_sub_f32_e32 v193, v193, v178
	v_pk_mul_f32 v[216:217], v[178:179], v[216:217] op_sel:[1,0]
	v_pk_mul_f32 v[192:193], v[178:179], v[192:193] op_sel:[1,0]
	v_pk_fma_f32 v[216:217], v[128:129], v[216:217], v[150:151]
	v_pk_fma_f32 v[192:193], v[130:131], v[192:193], v[152:153]
	v_pk_fma_f32 v[120:121], v[216:217], s[90:91], v[120:121] op_sel_hi:[1,0,1]
	v_pk_fma_f32 v[122:123], v[192:193], s[90:91], v[122:123] op_sel_hi:[1,0,1]
	v_cvt_pk_bf16_f32 v216, v120, v121
	v_cvt_pk_bf16_f32 v217, v122, v123
	global_store_dwordx2 v223, v[216:217], s[16:17] offset:0
	v_lshlrev_b32_e32 v218, 16, v194
	v_and_b32_e32 v219, 0xffff0000, v194
	v_lshlrev_b32_e32 v194, 16, v195
	v_and_b32_e32 v195, 0xffff0000, v195
	v_sub_f32_e32 v218, v218, v178
	v_sub_f32_e32 v219, v219, v178
	v_sub_f32_e32 v194, v194, v178
	v_sub_f32_e32 v195, v195, v178
	v_pk_mul_f32 v[218:219], v[178:179], v[218:219] op_sel:[1,0]
	v_pk_mul_f32 v[194:195], v[178:179], v[194:195] op_sel:[1,0]
	v_pk_fma_f32 v[218:219], v[132:133], v[218:219], v[154:155]
	v_pk_fma_f32 v[194:195], v[134:135], v[194:195], v[156:157]
	v_pk_fma_f32 v[104:105], v[218:219], s[90:91], v[104:105] op_sel_hi:[1,0,1]
	v_pk_fma_f32 v[106:107], v[194:195], s[90:91], v[106:107] op_sel_hi:[1,0,1]
	v_cvt_pk_bf16_f32 v218, v104, v105
	v_cvt_pk_bf16_f32 v219, v106, v107
	global_store_dwordx2 v223, v[218:219], s[16:17] offset:32
	v_lshlrev_b32_e32 v216, 16, v196
	v_and_b32_e32 v217, 0xffff0000, v196
	v_lshlrev_b32_e32 v196, 16, v197
	v_and_b32_e32 v197, 0xffff0000, v197
	v_sub_f32_e32 v216, v216, v178
	v_sub_f32_e32 v217, v217, v178
	v_sub_f32_e32 v196, v196, v178
	v_sub_f32_e32 v197, v197, v178
	v_pk_mul_f32 v[216:217], v[178:179], v[216:217] op_sel:[1,0]
	v_pk_mul_f32 v[196:197], v[178:179], v[196:197] op_sel:[1,0]
	v_pk_fma_f32 v[216:217], v[136:137], v[216:217], v[158:159]
	v_pk_fma_f32 v[196:197], v[138:139], v[196:197], v[160:161]
	v_pk_fma_f32 v[88:89], v[216:217], s[90:91], v[88:89] op_sel_hi:[1,0,1]
	v_pk_fma_f32 v[90:91], v[196:197], s[90:91], v[90:91] op_sel_hi:[1,0,1]
	v_cvt_pk_bf16_f32 v216, v88, v89
	v_cvt_pk_bf16_f32 v217, v90, v91
	global_store_dwordx2 v223, v[216:217], s[16:17] offset:256
	v_lshlrev_b32_e32 v218, 16, v198
	v_and_b32_e32 v219, 0xffff0000, v198
	v_lshlrev_b32_e32 v198, 16, v199
	v_and_b32_e32 v199, 0xffff0000, v199
	v_sub_f32_e32 v218, v218, v178
	v_sub_f32_e32 v219, v219, v178
	v_sub_f32_e32 v198, v198, v178
	v_sub_f32_e32 v199, v199, v178
	v_pk_mul_f32 v[218:219], v[178:179], v[218:219] op_sel:[1,0]
	v_pk_mul_f32 v[198:199], v[178:179], v[198:199] op_sel:[1,0]
	v_pk_fma_f32 v[218:219], v[146:147], v[218:219], v[174:175]
	v_pk_fma_f32 v[198:199], v[148:149], v[198:199], v[176:177]
	v_pk_fma_f32 v[72:73], v[218:219], s[90:91], v[72:73] op_sel_hi:[1,0,1]
	v_pk_fma_f32 v[74:75], v[198:199], s[90:91], v[74:75] op_sel_hi:[1,0,1]
	v_cvt_pk_bf16_f32 v218, v72, v73
	v_cvt_pk_bf16_f32 v219, v74, v75
	global_store_dwordx2 v223, v[218:219], s[16:17] offset:288
	s_add_u32 s16, s16, 0x8000
	s_addc_u32 s17, s17, 0
	global_load_dwordx2 v[178:179], v221, s[88:89] offset:1152
	global_load_dwordx2 v[192:193], v223, s[4:5] offset:0
	global_load_dwordx2 v[194:195], v223, s[4:5] offset:32
	global_load_dwordx2 v[196:197], v223, s[4:5] offset:256
	global_load_dwordx2 v[198:199], v223, s[4:5] offset:288
	s_add_u32 s4, s4, 0x8000
	s_addc_u32 s5, s5, 0
	s_waitcnt vmcnt(23)
	v_lshlrev_b32_e32 v216, 16, v200
	v_and_b32_e32 v217, 0xffff0000, v200
	v_lshlrev_b32_e32 v200, 16, v201
	v_and_b32_e32 v201, 0xffff0000, v201
	v_sub_f32_e32 v216, v216, v180
	v_sub_f32_e32 v217, v217, v180
	v_sub_f32_e32 v200, v200, v180
	v_sub_f32_e32 v201, v201, v180
	v_pk_mul_f32 v[216:217], v[180:181], v[216:217] op_sel:[1,0]
	v_pk_mul_f32 v[200:201], v[180:181], v[200:201] op_sel:[1,0]
	v_pk_fma_f32 v[216:217], v[128:129], v[216:217], v[150:151]
	v_pk_fma_f32 v[200:201], v[130:131], v[200:201], v[152:153]
	v_pk_fma_f32 v[116:117], v[216:217], s[90:91], v[116:117] op_sel_hi:[1,0,1]
	v_pk_fma_f32 v[118:119], v[200:201], s[90:91], v[118:119] op_sel_hi:[1,0,1]
	v_cvt_pk_bf16_f32 v216, v116, v117
	v_cvt_pk_bf16_f32 v217, v118, v119
	global_store_dwordx2 v223, v[216:217], s[16:17] offset:0
	v_lshlrev_b32_e32 v218, 16, v202
	v_and_b32_e32 v219, 0xffff0000, v202
	v_lshlrev_b32_e32 v202, 16, v203
	v_and_b32_e32 v203, 0xffff0000, v203
	v_sub_f32_e32 v218, v218, v180
	v_sub_f32_e32 v219, v219, v180
	v_sub_f32_e32 v202, v202, v180
	v_sub_f32_e32 v203, v203, v180
	v_pk_mul_f32 v[218:219], v[180:181], v[218:219] op_sel:[1,0]
	v_pk_mul_f32 v[202:203], v[180:181], v[202:203] op_sel:[1,0]
	v_pk_fma_f32 v[218:219], v[132:133], v[218:219], v[154:155]
	v_pk_fma_f32 v[202:203], v[134:135], v[202:203], v[156:157]
	v_pk_fma_f32 v[100:101], v[218:219], s[90:91], v[100:101] op_sel_hi:[1,0,1]
	v_pk_fma_f32 v[102:103], v[202:203], s[90:91], v[102:103] op_sel_hi:[1,0,1]
	v_cvt_pk_bf16_f32 v218, v100, v101
	v_cvt_pk_bf16_f32 v219, v102, v103
	global_store_dwordx2 v223, v[218:219], s[16:17] offset:32
	v_lshlrev_b32_e32 v216, 16, v204
	v_and_b32_e32 v217, 0xffff0000, v204
	v_lshlrev_b32_e32 v204, 16, v205
	v_and_b32_e32 v205, 0xffff0000, v205
	v_sub_f32_e32 v216, v216, v180
	v_sub_f32_e32 v217, v217, v180
	v_sub_f32_e32 v204, v204, v180
	v_sub_f32_e32 v205, v205, v180
	v_pk_mul_f32 v[216:217], v[180:181], v[216:217] op_sel:[1,0]
	v_pk_mul_f32 v[204:205], v[180:181], v[204:205] op_sel:[1,0]
	v_pk_fma_f32 v[216:217], v[136:137], v[216:217], v[158:159]
; __device__ __forceinline__ unsigned cvt_pk_bf16(float lo, float hi) { unsigned r; asm volatile("v_cvt_pk_bf16_f32 %0, %1, %2" : "=v"(r) : "v"(lo), "v"(hi)); return r; }
;     __device__ __forceinline__ void operator()(f32x4 (&acc)[2][2][4][2], const Unit& u, int wr, int wc, int fr, int fq) const {
;     ...
;                 for (int n = 0; n < 2; ++n) { const f32x4 g4 = *(const f32x4*)(gp + col0 + bj * HALF + n * 16), b4 = *(const f32x4*)(bp + col0 + bj * HALF + n * 16);
;                     u32x2 told[4];
;                     if (!Xin) {
; #pragma unroll
;                         for (int m = 0; m < 4; ++m) told[m] = *(const u32x2*)(YB + (size_t)(row0 + ai * HALF + m * 16) * 1024 + col0 + bj * HALF + n * 16);
;                     }
; #pragma unroll
;                     for (int m = 0; m < 4; ++m) { const size_t off = (size_t)(row0 + ai * HALF + m * 16) * 1024 + col0 + bj * HALF + n * 16;
;                         f32x4 yo;
;                         if (Xin) yo = *(const f32x4*)(Xin + off);
;                         else { const u32x2 t = told[m]; yo = (f32x4){__uint_as_float(t.x << 16), __uint_as_float(t.x & 0xffff0000u), __uint_as_float(t.y << 16), __uint_as_float(t.y & 0xffff0000u)}; }
;                         const f32x4 yn = ((yo - mu[m]) * rs[m] * g4 + b4) * alpha + acc[ai][bj][m][n];
;                         acc[ai][bj][m][n] = yn;
;                         if (Yout) *(f32x4*)(Yout + off) = yn;
;                         else { u32x2 w; w.x = cvt_pk_bf16(yn[0], yn[1]); w.y = cvt_pk_bf16(yn[2], yn[3]); *(u32x2*)(YB + off) = w; } } } }
	v_pk_fma_f32 v[204:205], v[138:139], v[204:205], v[160:161]
	v_pk_fma_f32 v[84:85], v[216:217], s[90:91], v[84:85] op_sel_hi:[1,0,1]
	v_pk_fma_f32 v[86:87], v[204:205], s[90:91], v[86:87] op_sel_hi:[1,0,1]
	v_cvt_pk_bf16_f32 v216, v84, v85
	v_cvt_pk_bf16_f32 v217, v86, v87
	global_store_dwordx2 v223, v[216:217], s[16:17] offset:256
	v_lshlrev_b32_e32 v218, 16, v206
	v_and_b32_e32 v219, 0xffff0000, v206
	v_lshlrev_b32_e32 v206, 16, v207
	v_and_b32_e32 v207, 0xffff0000, v207
	v_sub_f32_e32 v218, v218, v180
	v_sub_f32_e32 v219, v219, v180
	v_sub_f32_e32 v206, v206, v180
	v_sub_f32_e32 v207, v207, v180
	v_pk_mul_f32 v[218:219], v[180:181], v[218:219] op_sel:[1,0]
	v_pk_mul_f32 v[206:207], v[180:181], v[206:207] op_sel:[1,0]
	v_pk_fma_f32 v[218:219], v[146:147], v[218:219], v[174:175]
	v_pk_fma_f32 v[206:207], v[148:149], v[206:207], v[176:177]
	v_pk_fma_f32 v[68:69], v[218:219], s[90:91], v[68:69] op_sel_hi:[1,0,1]
	v_pk_fma_f32 v[70:71], v[206:207], s[90:91], v[70:71] op_sel_hi:[1,0,1]
	v_cvt_pk_bf16_f32 v218, v68, v69
	v_cvt_pk_bf16_f32 v219, v70, v71
	global_store_dwordx2 v223, v[218:219], s[16:17] offset:288
	s_add_u32 s16, s16, 0x8000
	s_addc_u32 s17, s17, 0
	global_load_dwordx2 v[180:181], v221, s[88:89] offset:1280
	global_load_dwordx2 v[200:201], v223, s[4:5] offset:0
	global_load_dwordx2 v[202:203], v223, s[4:5] offset:32
	global_load_dwordx2 v[204:205], v223, s[4:5] offset:256
	global_load_dwordx2 v[206:207], v223, s[4:5] offset:288
	s_add_u32 s4, s4, 0x8000
	s_addc_u32 s5, s5, 0
	s_waitcnt vmcnt(27)
	v_lshlrev_b32_e32 v216, 16, v208
	v_and_b32_e32 v217, 0xffff0000, v208
	v_lshlrev_b32_e32 v208, 16, v209
	v_and_b32_e32 v209, 0xffff0000, v209
	v_sub_f32_e32 v216, v216, v182
	v_sub_f32_e32 v217, v217, v182
	v_sub_f32_e32 v208, v208, v182
	v_sub_f32_e32 v209, v209, v182
	v_pk_mul_f32 v[216:217], v[182:183], v[216:217] op_sel:[1,0]
	v_pk_mul_f32 v[208:209], v[182:183], v[208:209] op_sel:[1,0]
	v_pk_fma_f32 v[216:217], v[128:129], v[216:217], v[150:151]
	v_pk_fma_f32 v[208:209], v[130:131], v[208:209], v[152:153]
	v_pk_fma_f32 v[112:113], v[216:217], s[90:91], v[112:113] op_sel_hi:[1,0,1]
	v_pk_fma_f32 v[114:115], v[208:209], s[90:91], v[114:115] op_sel_hi:[1,0,1]
	v_cvt_pk_bf16_f32 v216, v112, v113
	v_cvt_pk_bf16_f32 v217, v114, v115
	global_store_dwordx2 v223, v[216:217], s[16:17] offset:0
	v_lshlrev_b32_e32 v218, 16, v210
	v_and_b32_e32 v219, 0xffff0000, v210
	v_lshlrev_b32_e32 v210, 16, v211
	v_and_b32_e32 v211, 0xffff0000, v211
	v_sub_f32_e32 v218, v218, v182
	v_sub_f32_e32 v219, v219, v182
	v_sub_f32_e32 v210, v210, v182
	v_sub_f32_e32 v211, v211, v182
	v_pk_mul_f32 v[218:219], v[182:183], v[218:219] op_sel:[1,0]
	v_pk_mul_f32 v[210:211], v[182:183], v[210:211] op_sel:[1,0]
	v_pk_fma_f32 v[218:219], v[132:133], v[218:219], v[154:155]
	v_pk_fma_f32 v[210:211], v[134:135], v[210:211], v[156:157]
	v_pk_fma_f32 v[96:97], v[218:219], s[90:91], v[96:97] op_sel_hi:[1,0,1]
	v_pk_fma_f32 v[98:99], v[210:211], s[90:91], v[98:99] op_sel_hi:[1,0,1]
	v_cvt_pk_bf16_f32 v218, v96, v97
	v_cvt_pk_bf16_f32 v219, v98, v99
	global_store_dwordx2 v223, v[218:219], s[16:17] offset:32
	v_lshlrev_b32_e32 v216, 16, v212
	v_and_b32_e32 v217, 0xffff0000, v212
	v_lshlrev_b32_e32 v212, 16, v213
	v_and_b32_e32 v213, 0xffff0000, v213
	v_sub_f32_e32 v216, v216, v182
	v_sub_f32_e32 v217, v217, v182
	v_sub_f32_e32 v212, v212, v182
	v_sub_f32_e32 v213, v213, v182
	v_pk_mul_f32 v[216:217], v[182:183], v[216:217] op_sel:[1,0]
	v_pk_mul_f32 v[212:213], v[182:183], v[212:213] op_sel:[1,0]
	v_pk_fma_f32 v[216:217], v[136:137], v[216:217], v[158:159]
	v_pk_fma_f32 v[212:213], v[138:139], v[212:213], v[160:161]
	v_pk_fma_f32 v[80:81], v[216:217], s[90:91], v[80:81] op_sel_hi:[1,0,1]
	v_pk_fma_f32 v[82:83], v[212:213], s[90:91], v[82:83] op_sel_hi:[1,0,1]
	v_cvt_pk_bf16_f32 v216, v80, v81
	v_cvt_pk_bf16_f32 v217, v82, v83
	global_store_dwordx2 v223, v[216:217], s[16:17] offset:256
	v_lshlrev_b32_e32 v218, 16, v214
	v_and_b32_e32 v219, 0xffff0000, v214
	v_lshlrev_b32_e32 v214, 16, v215
	v_and_b32_e32 v215, 0xffff0000, v215
	v_sub_f32_e32 v218, v218, v182
	v_sub_f32_e32 v219, v219, v182
	v_sub_f32_e32 v214, v214, v182
	v_sub_f32_e32 v215, v215, v182
	v_pk_mul_f32 v[218:219], v[182:183], v[218:219] op_sel:[1,0]
	v_pk_mul_f32 v[214:215], v[182:183], v[214:215] op_sel:[1,0]
	v_pk_fma_f32 v[218:219], v[146:147], v[218:219], v[174:175]
	v_pk_fma_f32 v[214:215], v[148:149], v[214:215], v[176:177]
	v_pk_fma_f32 v[64:65], v[218:219], s[90:91], v[64:65] op_sel_hi:[1,0,1]
	v_pk_fma_f32 v[66:67], v[214:215], s[90:91], v[66:67] op_sel_hi:[1,0,1]
	v_cvt_pk_bf16_f32 v218, v64, v65
	v_cvt_pk_bf16_f32 v219, v66, v67
	global_store_dwordx2 v223, v[218:219], s[16:17] offset:288
	s_add_u32 s16, s16, 0x28000
	s_addc_u32 s17, s17, 0
	global_load_dwordx2 v[182:183], v221, s[88:89] offset:1408
	global_load_dwordx2 v[208:209], v223, s[4:5] offset:0
	global_load_dwordx2 v[210:211], v223, s[4:5] offset:32
	global_load_dwordx2 v[212:213], v223, s[4:5] offset:256
	global_load_dwordx2 v[214:215], v223, s[4:5] offset:288
	s_waitcnt vmcnt(27)
; __device__ __forceinline__ unsigned cvt_pk_bf16(float lo, float hi) { unsigned r; asm volatile("v_cvt_pk_bf16_f32 %0, %1, %2" : "=v"(r) : "v"(lo), "v"(hi)); return r; }
;     __device__ __forceinline__ void operator()(f32x4 (&acc)[2][2][4][2], const Unit& u, int wr, int wc, int fr, int fq) const {
;     ...
;                 for (int n = 0; n < 2; ++n) { const f32x4 g4 = *(const f32x4*)(gp + col0 + bj * HALF + n * 16), b4 = *(const f32x4*)(bp + col0 + bj * HALF + n * 16);
;                     u32x2 told[4];
;                     if (!Xin) {
; #pragma unroll
;                         for (int m = 0; m < 4; ++m) told[m] = *(const u32x2*)(YB + (size_t)(row0 + ai * HALF + m * 16) * 1024 + col0 + bj * HALF + n * 16);
;                     }
; #pragma unroll
;                     for (int m = 0; m < 4; ++m) { const size_t off = (size_t)(row0 + ai * HALF + m * 16) * 1024 + col0 + bj * HALF + n * 16;
;                         f32x4 yo;
;                         if (Xin) yo = *(const f32x4*)(Xin + off);
;                         else { const u32x2 t = told[m]; yo = (f32x4){__uint_as_float(t.x << 16), __uint_as_float(t.x & 0xffff0000u), __uint_as_float(t.y << 16), __uint_as_float(t.y & 0xffff0000u)}; }
;                         const f32x4 yn = ((yo - mu[m]) * rs[m] * g4 + b4) * alpha + acc[ai][bj][m][n];
;                         acc[ai][bj][m][n] = yn;
;                         if (Yout) *(f32x4*)(Yout + off) = yn;
;                         else { u32x2 w; w.x = cvt_pk_bf16(yn[0], yn[1]); w.y = cvt_pk_bf16(yn[2], yn[3]); *(u32x2*)(YB + off) = w; } } } }
	v_lshlrev_b32_e32 v216, 16, v184
	v_and_b32_e32 v217, 0xffff0000, v184
	v_lshlrev_b32_e32 v184, 16, v185
	v_and_b32_e32 v185, 0xffff0000, v185
	v_sub_f32_e32 v216, v216, v162
	v_sub_f32_e32 v217, v217, v162
	v_sub_f32_e32 v184, v184, v162
	v_sub_f32_e32 v185, v185, v162
	v_pk_mul_f32 v[216:217], v[162:163], v[216:217] op_sel:[1,0]
	v_pk_mul_f32 v[184:185], v[162:163], v[184:185] op_sel:[1,0]
	v_pk_fma_f32 v[216:217], v[128:129], v[216:217], v[150:151]
	v_pk_fma_f32 v[184:185], v[130:131], v[184:185], v[152:153]
	v_pk_fma_f32 v[60:61], v[216:217], s[90:91], v[60:61] op_sel_hi:[1,0,1]
	v_pk_fma_f32 v[62:63], v[184:185], s[90:91], v[62:63] op_sel_hi:[1,0,1]
	v_cvt_pk_bf16_f32 v216, v60, v61
	v_cvt_pk_bf16_f32 v217, v62, v63
	global_store_dwordx2 v223, v[216:217], s[16:17] offset:0
	v_lshlrev_b32_e32 v218, 16, v186
	v_and_b32_e32 v219, 0xffff0000, v186
	v_lshlrev_b32_e32 v186, 16, v187
	v_and_b32_e32 v187, 0xffff0000, v187
	v_sub_f32_e32 v218, v218, v162
	v_sub_f32_e32 v219, v219, v162
	v_sub_f32_e32 v186, v186, v162
	v_sub_f32_e32 v187, v187, v162
	v_pk_mul_f32 v[218:219], v[162:163], v[218:219] op_sel:[1,0]
	v_pk_mul_f32 v[186:187], v[162:163], v[186:187] op_sel:[1,0]
	v_pk_fma_f32 v[218:219], v[132:133], v[218:219], v[154:155]
	v_pk_fma_f32 v[186:187], v[134:135], v[186:187], v[156:157]
	v_pk_fma_f32 v[44:45], v[218:219], s[90:91], v[44:45] op_sel_hi:[1,0,1]
	v_pk_fma_f32 v[46:47], v[186:187], s[90:91], v[46:47] op_sel_hi:[1,0,1]
	v_cvt_pk_bf16_f32 v218, v44, v45
	v_cvt_pk_bf16_f32 v219, v46, v47
	global_store_dwordx2 v223, v[218:219], s[16:17] offset:32
	v_lshlrev_b32_e32 v216, 16, v188
	v_and_b32_e32 v217, 0xffff0000, v188
	v_lshlrev_b32_e32 v188, 16, v189
	v_and_b32_e32 v189, 0xffff0000, v189
	v_sub_f32_e32 v216, v216, v162
	v_sub_f32_e32 v217, v217, v162
	v_sub_f32_e32 v188, v188, v162
	v_sub_f32_e32 v189, v189, v162
	v_pk_mul_f32 v[216:217], v[162:163], v[216:217] op_sel:[1,0]
	v_pk_mul_f32 v[188:189], v[162:163], v[188:189] op_sel:[1,0]
	v_pk_fma_f32 v[216:217], v[136:137], v[216:217], v[158:159]
	v_pk_fma_f32 v[188:189], v[138:139], v[188:189], v[160:161]
	v_pk_fma_f32 v[28:29], v[216:217], s[90:91], v[28:29] op_sel_hi:[1,0,1]
	v_pk_fma_f32 v[30:31], v[188:189], s[90:91], v[30:31] op_sel_hi:[1,0,1]
	v_cvt_pk_bf16_f32 v216, v28, v29
	v_cvt_pk_bf16_f32 v217, v30, v31
	global_store_dwordx2 v223, v[216:217], s[16:17] offset:256
	v_lshlrev_b32_e32 v218, 16, v190
	v_and_b32_e32 v219, 0xffff0000, v190
	v_lshlrev_b32_e32 v190, 16, v191
	v_and_b32_e32 v191, 0xffff0000, v191
	v_sub_f32_e32 v218, v218, v162
	v_sub_f32_e32 v219, v219, v162
	v_sub_f32_e32 v190, v190, v162
	v_sub_f32_e32 v191, v191, v162
	v_pk_mul_f32 v[218:219], v[162:163], v[218:219] op_sel:[1,0]
	v_pk_mul_f32 v[190:191], v[162:163], v[190:191] op_sel:[1,0]
	v_pk_fma_f32 v[218:219], v[146:147], v[218:219], v[174:175]
	v_pk_fma_f32 v[190:191], v[148:149], v[190:191], v[176:177]
	v_pk_fma_f32 v[12:13], v[218:219], s[90:91], v[12:13] op_sel_hi:[1,0,1]
	v_pk_fma_f32 v[14:15], v[190:191], s[90:91], v[14:15] op_sel_hi:[1,0,1]
	v_cvt_pk_bf16_f32 v218, v12, v13
	v_cvt_pk_bf16_f32 v219, v14, v15
	global_store_dwordx2 v223, v[218:219], s[16:17] offset:288
	s_add_u32 s16, s16, 0x8000
	s_addc_u32 s17, s17, 0
	s_waitcnt vmcnt(22)
	v_lshlrev_b32_e32 v216, 16, v192
	v_and_b32_e32 v217, 0xffff0000, v192
	v_lshlrev_b32_e32 v192, 16, v193
	v_and_b32_e32 v193, 0xffff0000, v193
	v_sub_f32_e32 v216, v216, v178
	v_sub_f32_e32 v217, v217, v178
	v_sub_f32_e32 v192, v192, v178
	v_sub_f32_e32 v193, v193, v178
	v_pk_mul_f32 v[216:217], v[178:179], v[216:217] op_sel:[1,0]
	v_pk_mul_f32 v[192:193], v[178:179], v[192:193] op_sel:[1,0]
	v_pk_fma_f32 v[216:217], v[128:129], v[216:217], v[150:151]
	v_pk_fma_f32 v[192:193], v[130:131], v[192:193], v[152:153]
	v_pk_fma_f32 v[56:57], v[216:217], s[90:91], v[56:57] op_sel_hi:[1,0,1]
	v_pk_fma_f32 v[58:59], v[192:193], s[90:91], v[58:59] op_sel_hi:[1,0,1]
	v_cvt_pk_bf16_f32 v216, v56, v57
	v_cvt_pk_bf16_f32 v217, v58, v59
	global_store_dwordx2 v223, v[216:217], s[16:17] offset:0
	v_lshlrev_b32_e32 v218, 16, v194
	v_and_b32_e32 v219, 0xffff0000, v194
	v_lshlrev_b32_e32 v194, 16, v195
	v_and_b32_e32 v195, 0xffff0000, v195
	v_sub_f32_e32 v218, v218, v178
	v_sub_f32_e32 v219, v219, v178
	v_sub_f32_e32 v194, v194, v178
	v_sub_f32_e32 v195, v195, v178
	v_pk_mul_f32 v[218:219], v[178:179], v[218:219] op_sel:[1,0]
	v_pk_mul_f32 v[194:195], v[178:179], v[194:195] op_sel:[1,0]
	v_pk_fma_f32 v[218:219], v[132:133], v[218:219], v[154:155]
	v_pk_fma_f32 v[194:195], v[134:135], v[194:195], v[156:157]
	v_pk_fma_f32 v[40:41], v[218:219], s[90:91], v[40:41] op_sel_hi:[1,0,1]
	v_pk_fma_f32 v[42:43], v[194:195], s[90:91], v[42:43] op_sel_hi:[1,0,1]
	v_cvt_pk_bf16_f32 v218, v40, v41
	v_cvt_pk_bf16_f32 v219, v42, v43
	global_store_dwordx2 v223, v[218:219], s[16:17] offset:32
	v_lshlrev_b32_e32 v216, 16, v196
	v_and_b32_e32 v217, 0xffff0000, v196
	v_lshlrev_b32_e32 v196, 16, v197
	v_and_b32_e32 v197, 0xffff0000, v197
	v_sub_f32_e32 v216, v216, v178
	v_sub_f32_e32 v217, v217, v178
	v_sub_f32_e32 v196, v196, v178
	v_sub_f32_e32 v197, v197, v178
	v_pk_mul_f32 v[216:217], v[178:179], v[216:217] op_sel:[1,0]
	v_pk_mul_f32 v[196:197], v[178:179], v[196:197] op_sel:[1,0]
	v_pk_fma_f32 v[216:217], v[136:137], v[216:217], v[158:159]
	v_pk_fma_f32 v[196:197], v[138:139], v[196:197], v[160:161]
	v_pk_fma_f32 v[24:25], v[216:217], s[90:91], v[24:25] op_sel_hi:[1,0,1]
	v_pk_fma_f32 v[26:27], v[196:197], s[90:91], v[26:27] op_sel_hi:[1,0,1]
	v_cvt_pk_bf16_f32 v216, v24, v25
	v_cvt_pk_bf16_f32 v217, v26, v27
	global_store_dwordx2 v223, v[216:217], s[16:17] offset:256
	v_lshlrev_b32_e32 v218, 16, v198
	v_and_b32_e32 v219, 0xffff0000, v198
	v_lshlrev_b32_e32 v198, 16, v199
	v_and_b32_e32 v199, 0xffff0000, v199
	v_sub_f32_e32 v218, v218, v178
	v_sub_f32_e32 v219, v219, v178
	v_sub_f32_e32 v198, v198, v178
	v_sub_f32_e32 v199, v199, v178
	v_pk_mul_f32 v[218:219], v[178:179], v[218:219] op_sel:[1,0]
	v_pk_mul_f32 v[198:199], v[178:179], v[198:199] op_sel:[1,0]
	v_pk_fma_f32 v[218:219], v[146:147], v[218:219], v[174:175]
	v_pk_fma_f32 v[198:199], v[148:149], v[198:199], v[176:177]
	v_pk_fma_f32 v[8:9], v[218:219], s[90:91], v[8:9] op_sel_hi:[1,0,1]
	v_pk_fma_f32 v[10:11], v[198:199], s[90:91], v[10:11] op_sel_hi:[1,0,1]
	v_cvt_pk_bf16_f32 v218, v8, v9
	v_cvt_pk_bf16_f32 v219, v10, v11
	global_store_dwordx2 v223, v[218:219], s[16:17] offset:288
	s_add_u32 s16, s16, 0x8000
	s_addc_u32 s17, s17, 0
	s_waitcnt vmcnt(17)
; __device__ __forceinline__ unsigned cvt_pk_bf16(float lo, float hi) { unsigned r; asm volatile("v_cvt_pk_bf16_f32 %0, %1, %2" : "=v"(r) : "v"(lo), "v"(hi)); return r; }
;     __device__ __forceinline__ void operator()(f32x4 (&acc)[2][2][4][2], const Unit& u, int wr, int wc, int fr, int fq) const {
;     ...
;                 for (int n = 0; n < 2; ++n) { const f32x4 g4 = *(const f32x4*)(gp + col0 + bj * HALF + n * 16), b4 = *(const f32x4*)(bp + col0 + bj * HALF + n * 16);
;                     u32x2 told[4];
;                     if (!Xin) {
; #pragma unroll
;                         for (int m = 0; m < 4; ++m) told[m] = *(const u32x2*)(YB + (size_t)(row0 + ai * HALF + m * 16) * 1024 + col0 + bj * HALF + n * 16);
;                     }
; #pragma unroll
;                     for (int m = 0; m < 4; ++m) { const size_t off = (size_t)(row0 + ai * HALF + m * 16) * 1024 + col0 + bj * HALF + n * 16;
;                         f32x4 yo;
;                         if (Xin) yo = *(const f32x4*)(Xin + off);
;                         else { const u32x2 t = told[m]; yo = (f32x4){__uint_as_float(t.x << 16), __uint_as_float(t.x & 0xffff0000u), __uint_as_float(t.y << 16), __uint_as_float(t.y & 0xffff0000u)}; }
;                         const f32x4 yn = ((yo - mu[m]) * rs[m] * g4 + b4) * alpha + acc[ai][bj][m][n];
;                         acc[ai][bj][m][n] = yn;
;                         if (Yout) *(f32x4*)(Yout + off) = yn;
;                         else { u32x2 w; w.x = cvt_pk_bf16(yn[0], yn[1]); w.y = cvt_pk_bf16(yn[2], yn[3]); *(u32x2*)(YB + off) = w; } } } }
	v_lshlrev_b32_e32 v216, 16, v200
	v_and_b32_e32 v217, 0xffff0000, v200
	v_lshlrev_b32_e32 v200, 16, v201
	v_and_b32_e32 v201, 0xffff0000, v201
	v_sub_f32_e32 v216, v216, v180
	v_sub_f32_e32 v217, v217, v180
	v_sub_f32_e32 v200, v200, v180
	v_sub_f32_e32 v201, v201, v180
	v_pk_mul_f32 v[216:217], v[180:181], v[216:217] op_sel:[1,0]
	v_pk_mul_f32 v[200:201], v[180:181], v[200:201] op_sel:[1,0]
	v_pk_fma_f32 v[216:217], v[128:129], v[216:217], v[150:151]
	v_pk_fma_f32 v[200:201], v[130:131], v[200:201], v[152:153]
	v_pk_fma_f32 v[52:53], v[216:217], s[90:91], v[52:53] op_sel_hi:[1,0,1]
	v_pk_fma_f32 v[54:55], v[200:201], s[90:91], v[54:55] op_sel_hi:[1,0,1]
	v_cvt_pk_bf16_f32 v216, v52, v53
	v_cvt_pk_bf16_f32 v217, v54, v55
	global_store_dwordx2 v223, v[216:217], s[16:17] offset:0
	v_lshlrev_b32_e32 v218, 16, v202
	v_and_b32_e32 v219, 0xffff0000, v202
	v_lshlrev_b32_e32 v202, 16, v203
	v_and_b32_e32 v203, 0xffff0000, v203
	v_sub_f32_e32 v218, v218, v180
	v_sub_f32_e32 v219, v219, v180
	v_sub_f32_e32 v202, v202, v180
	v_sub_f32_e32 v203, v203, v180
	v_pk_mul_f32 v[218:219], v[180:181], v[218:219] op_sel:[1,0]
	v_pk_mul_f32 v[202:203], v[180:181], v[202:203] op_sel:[1,0]
	v_pk_fma_f32 v[218:219], v[132:133], v[218:219], v[154:155]
	v_pk_fma_f32 v[202:203], v[134:135], v[202:203], v[156:157]
	v_pk_fma_f32 v[36:37], v[218:219], s[90:91], v[36:37] op_sel_hi:[1,0,1]
	v_pk_fma_f32 v[38:39], v[202:203], s[90:91], v[38:39] op_sel_hi:[1,0,1]
	v_cvt_pk_bf16_f32 v218, v36, v37
	v_cvt_pk_bf16_f32 v219, v38, v39
	global_store_dwordx2 v223, v[218:219], s[16:17] offset:32
	v_lshlrev_b32_e32 v216, 16, v204
	v_and_b32_e32 v217, 0xffff0000, v204
	v_lshlrev_b32_e32 v204, 16, v205
	v_and_b32_e32 v205, 0xffff0000, v205
	v_sub_f32_e32 v216, v216, v180
	v_sub_f32_e32 v217, v217, v180
	v_sub_f32_e32 v204, v204, v180
	v_sub_f32_e32 v205, v205, v180
	v_pk_mul_f32 v[216:217], v[180:181], v[216:217] op_sel:[1,0]
	v_pk_mul_f32 v[204:205], v[180:181], v[204:205] op_sel:[1,0]
	v_pk_fma_f32 v[216:217], v[136:137], v[216:217], v[158:159]
	v_pk_fma_f32 v[204:205], v[138:139], v[204:205], v[160:161]
	v_pk_fma_f32 v[20:21], v[216:217], s[90:91], v[20:21] op_sel_hi:[1,0,1]
	v_pk_fma_f32 v[22:23], v[204:205], s[90:91], v[22:23] op_sel_hi:[1,0,1]
	v_cvt_pk_bf16_f32 v216, v20, v21
	v_cvt_pk_bf16_f32 v217, v22, v23
	global_store_dwordx2 v223, v[216:217], s[16:17] offset:256
	v_lshlrev_b32_e32 v218, 16, v206
	v_and_b32_e32 v219, 0xffff0000, v206
	v_lshlrev_b32_e32 v206, 16, v207
	v_and_b32_e32 v207, 0xffff0000, v207
	v_sub_f32_e32 v218, v218, v180
	v_sub_f32_e32 v219, v219, v180
	v_sub_f32_e32 v206, v206, v180
	v_sub_f32_e32 v207, v207, v180
	v_pk_mul_f32 v[218:219], v[180:181], v[218:219] op_sel:[1,0]
	v_pk_mul_f32 v[206:207], v[180:181], v[206:207] op_sel:[1,0]
	v_pk_fma_f32 v[218:219], v[146:147], v[218:219], v[174:175]
	v_pk_fma_f32 v[206:207], v[148:149], v[206:207], v[176:177]
	v_pk_fma_f32 v[4:5], v[218:219], s[90:91], v[4:5] op_sel_hi:[1,0,1]
	v_pk_fma_f32 v[6:7], v[206:207], s[90:91], v[6:7] op_sel_hi:[1,0,1]
	v_cvt_pk_bf16_f32 v218, v4, v5
	v_cvt_pk_bf16_f32 v219, v6, v7
	global_store_dwordx2 v223, v[218:219], s[16:17] offset:288
	s_add_u32 s16, s16, 0x8000
	s_addc_u32 s17, s17, 0
	s_waitcnt vmcnt(12)
	v_lshlrev_b32_e32 v216, 16, v208
	v_and_b32_e32 v217, 0xffff0000, v208
	v_lshlrev_b32_e32 v208, 16, v209
	v_and_b32_e32 v209, 0xffff0000, v209
	v_sub_f32_e32 v216, v216, v182
	v_sub_f32_e32 v217, v217, v182
	v_sub_f32_e32 v208, v208, v182
	v_sub_f32_e32 v209, v209, v182
	v_pk_mul_f32 v[216:217], v[182:183], v[216:217] op_sel:[1,0]
	v_pk_mul_f32 v[208:209], v[182:183], v[208:209] op_sel:[1,0]
	v_pk_fma_f32 v[216:217], v[128:129], v[216:217], v[150:151]
	v_pk_fma_f32 v[208:209], v[130:131], v[208:209], v[152:153]
	v_pk_fma_f32 v[48:49], v[216:217], s[90:91], v[48:49] op_sel_hi:[1,0,1]
	v_pk_fma_f32 v[50:51], v[208:209], s[90:91], v[50:51] op_sel_hi:[1,0,1]
	v_cvt_pk_bf16_f32 v216, v48, v49
	v_cvt_pk_bf16_f32 v217, v50, v51
	global_store_dwordx2 v223, v[216:217], s[16:17] offset:0
	v_lshlrev_b32_e32 v218, 16, v210
	v_and_b32_e32 v219, 0xffff0000, v210
	v_lshlrev_b32_e32 v210, 16, v211
	v_and_b32_e32 v211, 0xffff0000, v211
	v_sub_f32_e32 v218, v218, v182
	v_sub_f32_e32 v219, v219, v182
	v_sub_f32_e32 v210, v210, v182
	v_sub_f32_e32 v211, v211, v182
	v_pk_mul_f32 v[218:219], v[182:183], v[218:219] op_sel:[1,0]
	v_pk_mul_f32 v[210:211], v[182:183], v[210:211] op_sel:[1,0]
	v_pk_fma_f32 v[218:219], v[132:133], v[218:219], v[154:155]
	v_pk_fma_f32 v[210:211], v[134:135], v[210:211], v[156:157]
	v_pk_fma_f32 v[32:33], v[218:219], s[90:91], v[32:33] op_sel_hi:[1,0,1]
	v_pk_fma_f32 v[34:35], v[210:211], s[90:91], v[34:35] op_sel_hi:[1,0,1]
	v_cvt_pk_bf16_f32 v218, v32, v33
	v_cvt_pk_bf16_f32 v219, v34, v35
	global_store_dwordx2 v223, v[218:219], s[16:17] offset:32
	v_lshlrev_b32_e32 v216, 16, v212
	v_and_b32_e32 v217, 0xffff0000, v212
	v_lshlrev_b32_e32 v212, 16, v213
	v_and_b32_e32 v213, 0xffff0000, v213
	v_sub_f32_e32 v216, v216, v182
	v_sub_f32_e32 v217, v217, v182
	v_sub_f32_e32 v212, v212, v182
	v_sub_f32_e32 v213, v213, v182
	v_pk_mul_f32 v[216:217], v[182:183], v[216:217] op_sel:[1,0]
	v_pk_mul_f32 v[212:213], v[182:183], v[212:213] op_sel:[1,0]
	v_pk_fma_f32 v[216:217], v[136:137], v[216:217], v[158:159]
	v_pk_fma_f32 v[212:213], v[138:139], v[212:213], v[160:161]
	v_pk_fma_f32 v[16:17], v[216:217], s[90:91], v[16:17] op_sel_hi:[1,0,1]
	v_pk_fma_f32 v[18:19], v[212:213], s[90:91], v[18:19] op_sel_hi:[1,0,1]
	v_cvt_pk_bf16_f32 v216, v16, v17
	v_cvt_pk_bf16_f32 v217, v18, v19
	global_store_dwordx2 v223, v[216:217], s[16:17] offset:256
	v_lshlrev_b32_e32 v218, 16, v214
; __device__ __forceinline__ unsigned cvt_pk_bf16(float lo, float hi) { unsigned r; asm volatile("v_cvt_pk_bf16_f32 %0, %1, %2" : "=v"(r) : "v"(lo), "v"(hi)); return r; }
;     __device__ __forceinline__ void operator()(f32x4 (&acc)[2][2][4][2], const Unit& u, int wr, int wc, int fr, int fq) const {
;     ...
;                         const f32x4 yn = ((yo - mu[m]) * rs[m] * g4 + b4) * alpha + acc[ai][bj][m][n];
;                         acc[ai][bj][m][n] = yn;
;                         if (Yout) *(f32x4*)(Yout + off) = yn;
;                         else { u32x2 w; w.x = cvt_pk_bf16(yn[0], yn[1]); w.y = cvt_pk_bf16(yn[2], yn[3]); *(u32x2*)(YB + off) = w; } } } }
;     ...
;                 float s = 0.f;
; #pragma unroll
;                 for (int bj = 0; bj < 2; ++bj)
; #pragma unroll
;                     for (int n = 0; n < 2; ++n) { const f32x4 x = acc[ai][bj][m][n]; s += (x[0] + x[1]) + (x[2] + x[3]); }
;                 s += __shfl_xor(s, 16); s += __shfl_xor(s, 32);
	v_and_b32_e32 v219, 0xffff0000, v214
	v_lshlrev_b32_e32 v214, 16, v215
	v_and_b32_e32 v215, 0xffff0000, v215
	v_sub_f32_e32 v218, v218, v182
	v_sub_f32_e32 v219, v219, v182
	v_sub_f32_e32 v214, v214, v182
	v_sub_f32_e32 v215, v215, v182
	v_pk_mul_f32 v[218:219], v[182:183], v[218:219] op_sel:[1,0]
	v_pk_mul_f32 v[214:215], v[182:183], v[214:215] op_sel:[1,0]
	v_pk_fma_f32 v[218:219], v[146:147], v[218:219], v[174:175]
	v_pk_fma_f32 v[214:215], v[148:149], v[214:215], v[176:177]
	v_pk_fma_f32 v[0:1], v[218:219], s[90:91], v[0:1] op_sel_hi:[1,0,1]
	v_pk_fma_f32 v[2:3], v[214:215], s[90:91], v[2:3] op_sel_hi:[1,0,1]
	v_cvt_pk_bf16_f32 v218, v0, v1
	v_cvt_pk_bf16_f32 v219, v2, v3
	global_store_dwordx2 v223, v[218:219], s[16:17] offset:288
	v_xor_b32_e32 v205, 16, v230
	v_xor_b32_e32 v204, 32, v230
	v_lshlrev_b32_e32 v205, 2, v205
	v_lshlrev_b32_e32 v204, 2, v204
	v_add_f32_e32 v207, v124, v125
	v_add_f32_e32 v206, v126, v127
	v_add_f32_e32 v223, v207, v206
	v_add_f32_e32 v207, v108, v109
	v_add_f32_e32 v206, v110, v111
	v_add_f32_e32 v207, v207, v206
	v_add_f32_e32 v223, v223, v207
	v_add_f32_e32 v207, v92, v93
	v_add_f32_e32 v206, v94, v95
	v_add_f32_e32 v207, v207, v206
	v_add_f32_e32 v223, v223, v207
	v_add_f32_e32 v207, v76, v77
	v_add_f32_e32 v206, v78, v79
	v_add_f32_e32 v207, v207, v206
	v_add_f32_e32 v223, v223, v207
	v_add_f32_e32 v207, v120, v121
	v_add_f32_e32 v206, v122, v123
	v_add_f32_e32 v222, v207, v206
	v_add_f32_e32 v207, v104, v105
	v_add_f32_e32 v206, v106, v107
	v_add_f32_e32 v207, v207, v206
	v_add_f32_e32 v222, v222, v207
	v_add_f32_e32 v207, v88, v89
	v_add_f32_e32 v206, v90, v91
	v_add_f32_e32 v207, v207, v206
	v_add_f32_e32 v222, v222, v207
	v_add_f32_e32 v207, v72, v73
	v_add_f32_e32 v206, v74, v75
	v_add_f32_e32 v207, v207, v206
	v_add_f32_e32 v222, v222, v207
	v_add_f32_e32 v207, v116, v117
	v_add_f32_e32 v206, v118, v119
	v_add_f32_e32 v221, v207, v206
	v_add_f32_e32 v207, v100, v101
	v_add_f32_e32 v206, v102, v103
	v_add_f32_e32 v207, v207, v206
	v_add_f32_e32 v221, v221, v207
	v_add_f32_e32 v207, v84, v85
	v_add_f32_e32 v206, v86, v87
	v_add_f32_e32 v207, v207, v206
	v_add_f32_e32 v221, v221, v207
	v_add_f32_e32 v207, v68, v69
	v_add_f32_e32 v206, v70, v71
	v_add_f32_e32 v207, v207, v206
	v_add_f32_e32 v221, v221, v207
	v_add_f32_e32 v207, v112, v113
	v_add_f32_e32 v206, v114, v115
	v_add_f32_e32 v220, v207, v206
	v_add_f32_e32 v207, v96, v97
	v_add_f32_e32 v206, v98, v99
	v_add_f32_e32 v207, v207, v206
	v_add_f32_e32 v220, v220, v207
	v_add_f32_e32 v207, v80, v81
	v_add_f32_e32 v206, v82, v83
	v_add_f32_e32 v207, v207, v206
	v_add_f32_e32 v220, v220, v207
	v_add_f32_e32 v207, v64, v65
	v_add_f32_e32 v206, v66, v67
	v_add_f32_e32 v207, v207, v206
	v_add_f32_e32 v220, v220, v207
	v_add_f32_e32 v207, v60, v61
	v_add_f32_e32 v206, v62, v63
	v_add_f32_e32 v219, v207, v206
	v_add_f32_e32 v207, v44, v45
	v_add_f32_e32 v206, v46, v47
	v_add_f32_e32 v207, v207, v206
	v_add_f32_e32 v219, v219, v207
	v_add_f32_e32 v207, v28, v29
	v_add_f32_e32 v206, v30, v31
	v_add_f32_e32 v207, v207, v206
	v_add_f32_e32 v219, v219, v207
	v_add_f32_e32 v207, v12, v13
	v_add_f32_e32 v206, v14, v15
	v_add_f32_e32 v207, v207, v206
	v_add_f32_e32 v219, v219, v207
	v_add_f32_e32 v207, v56, v57
	v_add_f32_e32 v206, v58, v59
	v_add_f32_e32 v218, v207, v206
	v_add_f32_e32 v207, v40, v41
	v_add_f32_e32 v206, v42, v43
	v_add_f32_e32 v207, v207, v206
	v_add_f32_e32 v218, v218, v207
	v_add_f32_e32 v207, v24, v25
	v_add_f32_e32 v206, v26, v27
	v_add_f32_e32 v207, v207, v206
	v_add_f32_e32 v218, v218, v207
	v_add_f32_e32 v207, v8, v9
	v_add_f32_e32 v206, v10, v11
	v_add_f32_e32 v207, v207, v206
	v_add_f32_e32 v218, v218, v207
	v_add_f32_e32 v207, v52, v53
	v_add_f32_e32 v206, v54, v55
	v_add_f32_e32 v217, v207, v206
	v_add_f32_e32 v207, v36, v37
	v_add_f32_e32 v206, v38, v39
	v_add_f32_e32 v207, v207, v206
	v_add_f32_e32 v217, v217, v207
	v_add_f32_e32 v207, v20, v21
	v_add_f32_e32 v206, v22, v23
	v_add_f32_e32 v207, v207, v206
	v_add_f32_e32 v217, v217, v207
	v_add_f32_e32 v207, v4, v5
	v_add_f32_e32 v206, v6, v7
	v_add_f32_e32 v207, v207, v206
	v_add_f32_e32 v217, v217, v207
	v_add_f32_e32 v207, v48, v49
	v_add_f32_e32 v206, v50, v51
	v_add_f32_e32 v216, v207, v206
	v_add_f32_e32 v207, v32, v33
	v_add_f32_e32 v206, v34, v35
	v_add_f32_e32 v207, v207, v206
	v_add_f32_e32 v216, v216, v207
	v_add_f32_e32 v207, v16, v17
	v_add_f32_e32 v206, v18, v19
	v_add_f32_e32 v207, v207, v206
	v_add_f32_e32 v216, v216, v207
	v_add_f32_e32 v207, v0, v1
	v_add_f32_e32 v206, v2, v3
	v_add_f32_e32 v207, v207, v206
	v_add_f32_e32 v216, v216, v207
	ds_bpermute_b32 v215, v205, v223
	ds_bpermute_b32 v214, v205, v222
	ds_bpermute_b32 v213, v205, v221
	ds_bpermute_b32 v212, v205, v220
	ds_bpermute_b32 v211, v205, v219
	ds_bpermute_b32 v210, v205, v218
	ds_bpermute_b32 v209, v205, v217
	ds_bpermute_b32 v208, v205, v216
	s_waitcnt lgkmcnt(0)
	v_add_f32_e32 v223, v223, v215
	v_add_f32_e32 v222, v222, v214
	v_add_f32_e32 v221, v221, v213
	v_add_f32_e32 v220, v220, v212
	v_add_f32_e32 v219, v219, v211
	v_add_f32_e32 v218, v218, v210
	v_add_f32_e32 v217, v217, v209
	v_add_f32_e32 v216, v216, v208
	ds_bpermute_b32 v215, v204, v223
	ds_bpermute_b32 v214, v204, v222
	ds_bpermute_b32 v213, v204, v221
	ds_bpermute_b32 v212, v204, v220
	ds_bpermute_b32 v211, v204, v219
	ds_bpermute_b32 v210, v204, v218
	ds_bpermute_b32 v209, v204, v217
	ds_bpermute_b32 v208, v204, v216
	s_waitcnt lgkmcnt(0)
;     __device__ __forceinline__ void operator()(f32x4 (&acc)[2][2][4][2], const Unit& u, int wr, int wc, int fr, int fq) const {
;     ...
;                 s += __shfl_xor(s, 16); s += __shfl_xor(s, 32);
;                 const float mw = s * (1.0f / 64.0f); float q = 0.f;
; #pragma unroll
;                 for (int bj = 0; bj < 2; ++bj)
; #pragma unroll
;                     for (int n = 0; n < 2; ++n) { const f32x4 d = acc[ai][bj][m][n] - mw; q += (d[0] * d[0] + d[1] * d[1]) + (d[2] * d[2] + d[3] * d[3]); }
	v_add_f32_e32 v223, v223, v215
	v_add_f32_e32 v222, v222, v214
	v_add_f32_e32 v221, v221, v213
	v_add_f32_e32 v220, v220, v212
	v_add_f32_e32 v219, v219, v211
	v_add_f32_e32 v218, v218, v210
	v_add_f32_e32 v217, v217, v209
	v_add_f32_e32 v216, v216, v208
	v_fmac_f32_e32 v124, 0xbc800000, v223
	v_fmac_f32_e32 v125, 0xbc800000, v223
	v_fmac_f32_e32 v126, 0xbc800000, v223
	v_fmac_f32_e32 v127, 0xbc800000, v223
	v_mul_f32_e32 v207, v125, v125
	v_fmac_f32_e32 v207, v124, v124
	v_mul_f32_e32 v206, v127, v127
	v_fmac_f32_e32 v206, v126, v126
	v_add_f32_e32 v129, v207, v206
	v_fmac_f32_e32 v108, 0xbc800000, v223
	v_fmac_f32_e32 v109, 0xbc800000, v223
	v_fmac_f32_e32 v110, 0xbc800000, v223
	v_fmac_f32_e32 v111, 0xbc800000, v223
	v_mul_f32_e32 v207, v109, v109
	v_fmac_f32_e32 v207, v108, v108
	v_mul_f32_e32 v206, v111, v111
	v_fmac_f32_e32 v206, v110, v110
	v_add_f32_e32 v207, v207, v206
	v_add_f32_e32 v129, v129, v207
	v_fmac_f32_e32 v92, 0xbc800000, v223
	v_fmac_f32_e32 v93, 0xbc800000, v223
	v_fmac_f32_e32 v94, 0xbc800000, v223
	v_fmac_f32_e32 v95, 0xbc800000, v223
	v_mul_f32_e32 v207, v93, v93
	v_fmac_f32_e32 v207, v92, v92
	v_mul_f32_e32 v206, v95, v95
	v_fmac_f32_e32 v206, v94, v94
	v_add_f32_e32 v207, v207, v206
	v_add_f32_e32 v129, v129, v207
	v_fmac_f32_e32 v76, 0xbc800000, v223
	v_fmac_f32_e32 v77, 0xbc800000, v223
	v_fmac_f32_e32 v78, 0xbc800000, v223
	v_fmac_f32_e32 v79, 0xbc800000, v223
	v_mul_f32_e32 v207, v77, v77
	v_fmac_f32_e32 v207, v76, v76
	v_mul_f32_e32 v206, v79, v79
	v_fmac_f32_e32 v206, v78, v78
	v_add_f32_e32 v207, v207, v206
	v_add_f32_e32 v129, v129, v207
	v_fmac_f32_e32 v120, 0xbc800000, v222
	v_fmac_f32_e32 v121, 0xbc800000, v222
	v_fmac_f32_e32 v122, 0xbc800000, v222
	v_fmac_f32_e32 v123, 0xbc800000, v222
	v_mul_f32_e32 v207, v121, v121
	v_fmac_f32_e32 v207, v120, v120
	v_mul_f32_e32 v206, v123, v123
	v_fmac_f32_e32 v206, v122, v122
	v_add_f32_e32 v131, v207, v206
	v_fmac_f32_e32 v104, 0xbc800000, v222
	v_fmac_f32_e32 v105, 0xbc800000, v222
	v_fmac_f32_e32 v106, 0xbc800000, v222
	v_fmac_f32_e32 v107, 0xbc800000, v222
	v_mul_f32_e32 v207, v105, v105
	v_fmac_f32_e32 v207, v104, v104
	v_mul_f32_e32 v206, v107, v107
	v_fmac_f32_e32 v206, v106, v106
	v_add_f32_e32 v207, v207, v206
	v_add_f32_e32 v131, v131, v207
	v_fmac_f32_e32 v88, 0xbc800000, v222
	v_fmac_f32_e32 v89, 0xbc800000, v222
	v_fmac_f32_e32 v90, 0xbc800000, v222
	v_fmac_f32_e32 v91, 0xbc800000, v222
	v_mul_f32_e32 v207, v89, v89
	v_fmac_f32_e32 v207, v88, v88
	v_mul_f32_e32 v206, v91, v91
	v_fmac_f32_e32 v206, v90, v90
	v_add_f32_e32 v207, v207, v206
	v_add_f32_e32 v131, v131, v207
	v_fmac_f32_e32 v72, 0xbc800000, v222
	v_fmac_f32_e32 v73, 0xbc800000, v222
	v_fmac_f32_e32 v74, 0xbc800000, v222
	v_fmac_f32_e32 v75, 0xbc800000, v222
	v_mul_f32_e32 v207, v73, v73
	v_fmac_f32_e32 v207, v72, v72
	v_mul_f32_e32 v206, v75, v75
	v_fmac_f32_e32 v206, v74, v74
	v_add_f32_e32 v207, v207, v206
	v_add_f32_e32 v131, v131, v207
	v_fmac_f32_e32 v116, 0xbc800000, v221
	v_fmac_f32_e32 v117, 0xbc800000, v221
	v_fmac_f32_e32 v118, 0xbc800000, v221
	v_fmac_f32_e32 v119, 0xbc800000, v221
	v_mul_f32_e32 v207, v117, v117
	v_fmac_f32_e32 v207, v116, v116
	v_mul_f32_e32 v206, v119, v119
	v_fmac_f32_e32 v206, v118, v118
	v_add_f32_e32 v133, v207, v206
	v_fmac_f32_e32 v100, 0xbc800000, v221
	v_fmac_f32_e32 v101, 0xbc800000, v221
	v_fmac_f32_e32 v102, 0xbc800000, v221
	v_fmac_f32_e32 v103, 0xbc800000, v221
	v_mul_f32_e32 v207, v101, v101
	v_fmac_f32_e32 v207, v100, v100
	v_mul_f32_e32 v206, v103, v103
	v_fmac_f32_e32 v206, v102, v102
	v_add_f32_e32 v207, v207, v206
	v_add_f32_e32 v133, v133, v207
	v_fmac_f32_e32 v84, 0xbc800000, v221
	v_fmac_f32_e32 v85, 0xbc800000, v221
	v_fmac_f32_e32 v86, 0xbc800000, v221
	v_fmac_f32_e32 v87, 0xbc800000, v221
	v_mul_f32_e32 v207, v85, v85
	v_fmac_f32_e32 v207, v84, v84
	v_mul_f32_e32 v206, v87, v87
	v_fmac_f32_e32 v206, v86, v86
	v_add_f32_e32 v207, v207, v206
	v_add_f32_e32 v133, v133, v207
	v_fmac_f32_e32 v68, 0xbc800000, v221
	v_fmac_f32_e32 v69, 0xbc800000, v221
	v_fmac_f32_e32 v70, 0xbc800000, v221
	v_fmac_f32_e32 v71, 0xbc800000, v221
	v_mul_f32_e32 v207, v69, v69
	v_fmac_f32_e32 v207, v68, v68
	v_mul_f32_e32 v206, v71, v71
	v_fmac_f32_e32 v206, v70, v70
	v_add_f32_e32 v207, v207, v206
	v_add_f32_e32 v133, v133, v207
	v_fmac_f32_e32 v112, 0xbc800000, v220
	v_fmac_f32_e32 v113, 0xbc800000, v220
	v_fmac_f32_e32 v114, 0xbc800000, v220
	v_fmac_f32_e32 v115, 0xbc800000, v220
	v_mul_f32_e32 v207, v113, v113
	v_fmac_f32_e32 v207, v112, v112
	v_mul_f32_e32 v206, v115, v115
	v_fmac_f32_e32 v206, v114, v114
	v_add_f32_e32 v135, v207, v206
	v_fmac_f32_e32 v96, 0xbc800000, v220
	v_fmac_f32_e32 v97, 0xbc800000, v220
	v_fmac_f32_e32 v98, 0xbc800000, v220
	v_fmac_f32_e32 v99, 0xbc800000, v220
	v_mul_f32_e32 v207, v97, v97
	v_fmac_f32_e32 v207, v96, v96
	v_mul_f32_e32 v206, v99, v99
	v_fmac_f32_e32 v206, v98, v98
	v_add_f32_e32 v207, v207, v206
	v_add_f32_e32 v135, v135, v207
	v_fmac_f32_e32 v80, 0xbc800000, v220
	v_fmac_f32_e32 v81, 0xbc800000, v220
	v_fmac_f32_e32 v82, 0xbc800000, v220
	v_fmac_f32_e32 v83, 0xbc800000, v220
	v_mul_f32_e32 v207, v81, v81
	v_fmac_f32_e32 v207, v80, v80
	v_mul_f32_e32 v206, v83, v83
	v_fmac_f32_e32 v206, v82, v82
	v_add_f32_e32 v207, v207, v206
	v_add_f32_e32 v135, v135, v207
	v_fmac_f32_e32 v64, 0xbc800000, v220
	v_fmac_f32_e32 v65, 0xbc800000, v220
	v_fmac_f32_e32 v66, 0xbc800000, v220
	v_fmac_f32_e32 v67, 0xbc800000, v220
	v_mul_f32_e32 v207, v65, v65
	v_fmac_f32_e32 v207, v64, v64
	v_mul_f32_e32 v206, v67, v67
	v_fmac_f32_e32 v206, v66, v66
	v_add_f32_e32 v207, v207, v206
	v_add_f32_e32 v135, v135, v207
	v_fmac_f32_e32 v60, 0xbc800000, v219
;     __device__ __forceinline__ void operator()(f32x4 (&acc)[2][2][4][2], const Unit& u, int wr, int wc, int fr, int fq) const {
;     ...
;                 const float mw = s * (1.0f / 64.0f); float q = 0.f;
; #pragma unroll
;                 for (int bj = 0; bj < 2; ++bj)
; #pragma unroll
;                     for (int n = 0; n < 2; ++n) { const f32x4 d = acc[ai][bj][m][n] - mw; q += (d[0] * d[0] + d[1] * d[1]) + (d[2] * d[2] + d[3] * d[3]); }
;                 q += __shfl_xor(q, 16); q += __shfl_xor(q, 32);
;                 if (fq == 0) P[(ai * HALF + wr * 64 + m * 16 + fr) * 4 + wc] = (f32x2){mw, q};
	v_fmac_f32_e32 v61, 0xbc800000, v219
	v_fmac_f32_e32 v62, 0xbc800000, v219
	v_fmac_f32_e32 v63, 0xbc800000, v219
	v_mul_f32_e32 v207, v61, v61
	v_fmac_f32_e32 v207, v60, v60
	v_mul_f32_e32 v206, v63, v63
	v_fmac_f32_e32 v206, v62, v62
	v_add_f32_e32 v137, v207, v206
	v_fmac_f32_e32 v44, 0xbc800000, v219
	v_fmac_f32_e32 v45, 0xbc800000, v219
	v_fmac_f32_e32 v46, 0xbc800000, v219
	v_fmac_f32_e32 v47, 0xbc800000, v219
	v_mul_f32_e32 v207, v45, v45
	v_fmac_f32_e32 v207, v44, v44
	v_mul_f32_e32 v206, v47, v47
	v_fmac_f32_e32 v206, v46, v46
	v_add_f32_e32 v207, v207, v206
	v_add_f32_e32 v137, v137, v207
	v_fmac_f32_e32 v28, 0xbc800000, v219
	v_fmac_f32_e32 v29, 0xbc800000, v219
	v_fmac_f32_e32 v30, 0xbc800000, v219
	v_fmac_f32_e32 v31, 0xbc800000, v219
	v_mul_f32_e32 v207, v29, v29
	v_fmac_f32_e32 v207, v28, v28
	v_mul_f32_e32 v206, v31, v31
	v_fmac_f32_e32 v206, v30, v30
	v_add_f32_e32 v207, v207, v206
	v_add_f32_e32 v137, v137, v207
	v_fmac_f32_e32 v12, 0xbc800000, v219
	v_fmac_f32_e32 v13, 0xbc800000, v219
	v_fmac_f32_e32 v14, 0xbc800000, v219
	v_fmac_f32_e32 v15, 0xbc800000, v219
	v_mul_f32_e32 v207, v13, v13
	v_fmac_f32_e32 v207, v12, v12
	v_mul_f32_e32 v206, v15, v15
	v_fmac_f32_e32 v206, v14, v14
	v_add_f32_e32 v207, v207, v206
	v_add_f32_e32 v137, v137, v207
	v_fmac_f32_e32 v56, 0xbc800000, v218
	v_fmac_f32_e32 v57, 0xbc800000, v218
	v_fmac_f32_e32 v58, 0xbc800000, v218
	v_fmac_f32_e32 v59, 0xbc800000, v218
	v_mul_f32_e32 v207, v57, v57
	v_fmac_f32_e32 v207, v56, v56
	v_mul_f32_e32 v206, v59, v59
	v_fmac_f32_e32 v206, v58, v58
	v_add_f32_e32 v139, v207, v206
	v_fmac_f32_e32 v40, 0xbc800000, v218
	v_fmac_f32_e32 v41, 0xbc800000, v218
	v_fmac_f32_e32 v42, 0xbc800000, v218
	v_fmac_f32_e32 v43, 0xbc800000, v218
	v_mul_f32_e32 v207, v41, v41
	v_fmac_f32_e32 v207, v40, v40
	v_mul_f32_e32 v206, v43, v43
	v_fmac_f32_e32 v206, v42, v42
	v_add_f32_e32 v207, v207, v206
	v_add_f32_e32 v139, v139, v207
	v_fmac_f32_e32 v24, 0xbc800000, v218
	v_fmac_f32_e32 v25, 0xbc800000, v218
	v_fmac_f32_e32 v26, 0xbc800000, v218
	v_fmac_f32_e32 v27, 0xbc800000, v218
	v_mul_f32_e32 v207, v25, v25
	v_fmac_f32_e32 v207, v24, v24
	v_mul_f32_e32 v206, v27, v27
	v_fmac_f32_e32 v206, v26, v26
	v_add_f32_e32 v207, v207, v206
	v_add_f32_e32 v139, v139, v207
	v_fmac_f32_e32 v8, 0xbc800000, v218
	v_fmac_f32_e32 v9, 0xbc800000, v218
	v_fmac_f32_e32 v10, 0xbc800000, v218
	v_fmac_f32_e32 v11, 0xbc800000, v218
	v_mul_f32_e32 v207, v9, v9
	v_fmac_f32_e32 v207, v8, v8
	v_mul_f32_e32 v206, v11, v11
	v_fmac_f32_e32 v206, v10, v10
	v_add_f32_e32 v207, v207, v206
	v_add_f32_e32 v139, v139, v207
	v_fmac_f32_e32 v52, 0xbc800000, v217
	v_fmac_f32_e32 v53, 0xbc800000, v217
	v_fmac_f32_e32 v54, 0xbc800000, v217
	v_fmac_f32_e32 v55, 0xbc800000, v217
	v_mul_f32_e32 v207, v53, v53
	v_fmac_f32_e32 v207, v52, v52
	v_mul_f32_e32 v206, v55, v55
	v_fmac_f32_e32 v206, v54, v54
	v_add_f32_e32 v147, v207, v206
	v_fmac_f32_e32 v36, 0xbc800000, v217
	v_fmac_f32_e32 v37, 0xbc800000, v217
	v_fmac_f32_e32 v38, 0xbc800000, v217
	v_fmac_f32_e32 v39, 0xbc800000, v217
	v_mul_f32_e32 v207, v37, v37
	v_fmac_f32_e32 v207, v36, v36
	v_mul_f32_e32 v206, v39, v39
	v_fmac_f32_e32 v206, v38, v38
	v_add_f32_e32 v207, v207, v206
	v_add_f32_e32 v147, v147, v207
	v_fmac_f32_e32 v20, 0xbc800000, v217
	v_fmac_f32_e32 v21, 0xbc800000, v217
	v_fmac_f32_e32 v22, 0xbc800000, v217
	v_fmac_f32_e32 v23, 0xbc800000, v217
	v_mul_f32_e32 v207, v21, v21
	v_fmac_f32_e32 v207, v20, v20
	v_mul_f32_e32 v206, v23, v23
	v_fmac_f32_e32 v206, v22, v22
	v_add_f32_e32 v207, v207, v206
	v_add_f32_e32 v147, v147, v207
	v_fmac_f32_e32 v4, 0xbc800000, v217
	v_fmac_f32_e32 v5, 0xbc800000, v217
	v_fmac_f32_e32 v6, 0xbc800000, v217
	v_fmac_f32_e32 v7, 0xbc800000, v217
	v_mul_f32_e32 v207, v5, v5
	v_fmac_f32_e32 v207, v4, v4
	v_mul_f32_e32 v206, v7, v7
	v_fmac_f32_e32 v206, v6, v6
	v_add_f32_e32 v207, v207, v206
	v_add_f32_e32 v147, v147, v207
	v_fmac_f32_e32 v48, 0xbc800000, v216
	v_fmac_f32_e32 v49, 0xbc800000, v216
	v_fmac_f32_e32 v50, 0xbc800000, v216
	v_fmac_f32_e32 v51, 0xbc800000, v216
	v_mul_f32_e32 v207, v49, v49
	v_fmac_f32_e32 v207, v48, v48
	v_mul_f32_e32 v206, v51, v51
	v_fmac_f32_e32 v206, v50, v50
	v_add_f32_e32 v149, v207, v206
	v_fmac_f32_e32 v32, 0xbc800000, v216
	v_fmac_f32_e32 v33, 0xbc800000, v216
	v_fmac_f32_e32 v34, 0xbc800000, v216
	v_fmac_f32_e32 v35, 0xbc800000, v216
	v_mul_f32_e32 v207, v33, v33
	v_fmac_f32_e32 v207, v32, v32
	v_mul_f32_e32 v206, v35, v35
	v_fmac_f32_e32 v206, v34, v34
	v_add_f32_e32 v207, v207, v206
	v_add_f32_e32 v149, v149, v207
	v_fmac_f32_e32 v16, 0xbc800000, v216
	v_fmac_f32_e32 v17, 0xbc800000, v216
	v_fmac_f32_e32 v18, 0xbc800000, v216
	v_fmac_f32_e32 v19, 0xbc800000, v216
	v_mul_f32_e32 v207, v17, v17
	v_fmac_f32_e32 v207, v16, v16
	v_mul_f32_e32 v206, v19, v19
	v_fmac_f32_e32 v206, v18, v18
	v_add_f32_e32 v207, v207, v206
	v_add_f32_e32 v149, v149, v207
	v_fmac_f32_e32 v0, 0xbc800000, v216
	v_fmac_f32_e32 v1, 0xbc800000, v216
	v_fmac_f32_e32 v2, 0xbc800000, v216
	v_fmac_f32_e32 v3, 0xbc800000, v216
	v_mul_f32_e32 v207, v1, v1
	v_fmac_f32_e32 v207, v0, v0
	v_mul_f32_e32 v206, v3, v3
	v_fmac_f32_e32 v206, v2, v2
	v_add_f32_e32 v207, v207, v206
	v_add_f32_e32 v149, v149, v207
	ds_bpermute_b32 v215, v205, v129
	ds_bpermute_b32 v214, v205, v131
	ds_bpermute_b32 v213, v205, v133
	ds_bpermute_b32 v212, v205, v135
	ds_bpermute_b32 v211, v205, v137
	ds_bpermute_b32 v210, v205, v139
	ds_bpermute_b32 v209, v205, v147
	ds_bpermute_b32 v208, v205, v149
	s_waitcnt lgkmcnt(0)
	v_add_f32_e32 v129, v129, v215
	v_add_f32_e32 v131, v131, v214
	v_add_f32_e32 v133, v133, v213
	v_add_f32_e32 v135, v135, v212
	v_add_f32_e32 v137, v137, v211
	v_add_f32_e32 v139, v139, v210
	v_add_f32_e32 v147, v147, v209
	v_add_f32_e32 v149, v149, v208
	ds_bpermute_b32 v215, v204, v129
	ds_bpermute_b32 v214, v204, v131
	ds_bpermute_b32 v213, v204, v133
	ds_bpermute_b32 v212, v204, v135
	ds_bpermute_b32 v211, v204, v137
	ds_bpermute_b32 v210, v204, v139
	ds_bpermute_b32 v209, v204, v147
	ds_bpermute_b32 v208, v204, v149
	s_waitcnt lgkmcnt(0)
	v_add_f32_e32 v129, v129, v215
	v_add_f32_e32 v131, v131, v214
	v_add_f32_e32 v133, v133, v213
	v_add_f32_e32 v135, v135, v212
	v_add_f32_e32 v137, v137, v211
	v_add_f32_e32 v139, v139, v210
	v_add_f32_e32 v147, v147, v209
	v_add_f32_e32 v149, v149, v208
	v_mul_f32_e32 v128, 0x3c800000, v223
	v_mul_f32_e32 v130, 0x3c800000, v222
	v_mul_f32_e32 v132, 0x3c800000, v221
	v_mul_f32_e32 v134, 0x3c800000, v220
	v_mul_f32_e32 v136, 0x3c800000, v219
	v_mul_f32_e32 v138, 0x3c800000, v218
	v_mul_f32_e32 v146, 0x3c800000, v217
	v_mul_f32_e32 v148, 0x3c800000, v216
	s_and_saveexec_b64 s[4:5], s[8:9]
	ds_write_b64 v234, v[128:129]
	ds_write_b64 v234, v[130:131] offset:512
	ds_write_b64 v234, v[132:133] offset:1024
	ds_write_b64 v234, v[134:135] offset:1536
	ds_write_b64 v234, v[136:137] offset:4096
	ds_write_b64 v234, v[138:139] offset:4608
	ds_write_b64 v234, v[146:147] offset:5120
	ds_write_b64 v234, v[148:149] offset:5632
	s_or_b64 exec, exec, s[4:5]
	s_branch .Lres_join_a
